# GLA decay log writes: sixteen bank-conflicted 32-bit LDS writes per thread gathered into four 128-bit writes (pass1 and pass3)
# baseline (speedup 1.0000x reference)
.LBB0_595:
	s_mul_hi_i32 s0, s8, 0x3e0f83e1
	s_lshr_b32 s1, s0, 31
	s_ashr_i32 s0, s0, 5
	s_add_i32 s0, s0, s1
	s_mul_i32 s1, s0, 0x84
	s_sub_i32 s20, s8, s1
	s_and_b32 s19, s0, 1
	s_bfe_u32 s21, s0, 0x20001
	s_lshl_b32 s1, s20, 6
	s_cmp_lt_i32 s20, 4
	s_cselect_b32 s9, s7, s6
	v_mov_b32_e32 v16, v207
	s_add_i32 s9, s9, s1
	v_mov_b32_e32 v10, v207
	s_cmp_eq_u32 s19, 0
	s_barrier
	s_cselect_b64 s[42:43], -1, 0
	v_ashrrev_i32_e32 v4, 3, v10
	v_lshlrev_b32_e32 v0, 4, v10
	s_cmp_eq_u32 s19, 1
	v_and_b32_e32 v2, 0x70, v0
	v_add_u32_e32 v3, s9, v4
	v_mov_b64_e32 v[0:1], s[36:37]
	s_cselect_b64 s[2:3], -1, 0
	s_and_b32 s22, s0, -8
	v_mad_i64_i32 v[0:1], s[0:1], v3, s14, v[0:1]
	s_lshl_b32 s26, s21, 8
	s_lshl_b32 s18, s21, 7
	v_lshl_add_u64 v[0:1], v[0:1], 0, s[26:27]
	v_lshlrev_b32_e32 v128, 1, v2
	v_lshlrev_b32_e32 v3, 9, v4
	v_lshlrev_b32_e32 v5, 2, v2
	v_lshl_add_u64 v[0:1], v[0:1], 0, v[128:129]
	s_mov_b64 s[0:1], -1
	s_movk_i32 s100, 0xe00
	s_cmp_eq_u32 s22, 8
	s_cselect_b32 s100, 0x400, s100
	s_lshl_b32 s101, s21, 7
	s_add_i32 s100, s100, s101
	s_lshl_b32 s100, s100, 1
	s_mov_b32 s101, 0
	v_and_b32_e32 v162, 63, v207
	v_or_b32_e32 v162, s9, v162
	v_mul_u32_u24_e32 v162, 0x1200, v162
	v_mov_b32_e32 v163, 0
	v_lshl_add_u64 v[162:163], v[162:163], 1, s[36:37]
	v_lshl_add_u64 v[162:163], v[162:163], 0, s[100:101]
	v_ashrrev_i32_e32 v164, 2, v207
	v_and_b32_e32 v164, -16, v164
	v_mov_b32_e32 v165, 0
	v_lshl_add_u64 v[162:163], v[164:165], 1, v[162:163]
	global_load_dwordx4 v[154:157], v[162:163], off
	global_load_dwordx4 v[158:161], v[162:163], off offset:16
	s_cmp_lg_u32 s22, 8
	v_add3_u32 v5, 0, v3, v5
	s_cbranch_scc0 .LBB0_613
	s_and_b64 s[0:1], s[42:43], exec
	s_cselect_b32 s26, s15, 0x1800
	v_lshl_add_u64 v[12:13], v[0:1], 0, s[26:27]
	global_load_dwordx4 v[6:9], v[12:13], off
	global_load_dwordx4 v[26:29], v[12:13], off offset:16
	v_or_b32_e32 v2, s18, v2
	v_lshlrev_b32_e32 v128, 2, v2
	v_lshl_add_u64 v[2:3], s[78:79], 0, v[128:129]
	s_waitcnt vmcnt(0) lgkmcnt(0)
	v_lshlrev_b32_e32 v11, 16, v6
	v_and_b32_e32 v25, 0xffff0000, v6
	global_load_dword v6, v[2:3], off
	v_lshlrev_b32_e32 v15, 16, v8
	v_and_b32_e32 v12, 0xffff0000, v8
	v_mul_f32_e32 v8, 0xbfb8aa3b, v11
	v_exp_f32_e32 v8, v8
	v_lshlrev_b32_e32 v20, 16, v9
	v_and_b32_e32 v17, 0xffff0000, v9
	v_lshlrev_b32_e32 v24, 16, v26
	v_add_f32_e32 v8, 1.0, v8
	v_rcp_f32_e32 v11, v8
	v_and_b32_e32 v21, 0xffff0000, v26
	v_lshlrev_b32_e32 v23, 16, v27
	v_and_b32_e32 v22, 0xffff0000, v27
	v_lshlrev_b32_e32 v19, 16, v28
	v_and_b32_e32 v18, 0xffff0000, v28
	v_mul_f32_e32 v8, 1.0, v11
	v_mul_f32_e32 v9, 0xbfb8aa3b, v25
	v_exp_f32_e32 v9, v9
	v_lshlrev_b32_e32 v30, 16, v7
	v_and_b32_e32 v31, 0xffff0000, v7
	v_lshlrev_b32_e32 v14, 16, v29
	v_add_f32_e32 v9, 1.0, v9
	v_rcp_f32_e32 v25, v9
	v_and_b32_e32 v13, 0xffff0000, v29
	v_mul_f32_e32 v15, 0xbfb8aa3b, v15
	v_exp_f32_e32 v15, v15
	v_mul_f32_e32 v9, 1.0, v25
	v_mul_f32_e32 v11, 0xbfb8aa3b, v30
	v_exp_f32_e32 v11, v11
	v_add_f32_e32 v15, 1.0, v15
	v_mul_f32_e32 v12, 0xbfb8aa3b, v12
	v_exp_f32_e32 v12, v12
	v_add_f32_e32 v11, 1.0, v11
	v_mul_f32_e32 v20, 0xbfb8aa3b, v20
	v_exp_f32_e32 v20, v20
	v_add_f32_e32 v12, 1.0, v12
	v_mul_f32_e32 v17, 0xbfb8aa3b, v17
	v_exp_f32_e32 v17, v17
	v_add_f32_e32 v20, 1.0, v20
	v_mul_f32_e32 v24, 0xbfb8aa3b, v24
	v_exp_f32_e32 v24, v24
	v_add_f32_e32 v17, 1.0, v17
	v_mul_f32_e32 v21, 0xbfb8aa3b, v21
	v_exp_f32_e32 v21, v21
	v_add_f32_e32 v24, 1.0, v24
	v_mul_f32_e32 v23, 0xbfb8aa3b, v23
	v_exp_f32_e32 v23, v23
	v_add_f32_e32 v21, 1.0, v21
	v_mul_f32_e32 v22, 0xbfb8aa3b, v22
	v_exp_f32_e32 v22, v22
	v_add_f32_e32 v23, 1.0, v23
	v_mul_f32_e32 v19, 0xbfb8aa3b, v19
	v_exp_f32_e32 v19, v19
	v_add_f32_e32 v22, 1.0, v22
	v_mul_f32_e32 v18, 0xbfb8aa3b, v18
	v_exp_f32_e32 v18, v18
	v_add_f32_e32 v19, 1.0, v19
	v_mul_f32_e32 v14, 0xbfb8aa3b, v14
	s_waitcnt vmcnt(0) lgkmcnt(0)
	v_sub_f32_e32 v7, 1.0, v6
	v_fmac_f32_e32 v6, v7, v8
	v_cmp_gt_f32_e32 vcc, s12, v6
	v_add_f32_e32 v18, 1.0, v18
	v_exp_f32_e32 v14, v14
	v_cndmask_b32_e64 v7, 0, 32, vcc
	v_ldexp_f32 v7, v6, v7
	v_log_f32_e32 v7, v7
	v_add_f32_e32 v14, 1.0, v14
	v_mul_f32_e32 v13, 0xbfb8aa3b, v13
	v_exp_f32_e32 v13, v13
	v_mul_f32_e32 v8, 0x3f317217, v7
	v_fma_f32 v8, v7, s86, -v8
	v_fmac_f32_e32 v8, 0x3377d1cf, v7
	v_fmac_f32_e32 v8, 0x3f317217, v7
	v_cmp_lt_f32_e64 s[0:1], |v7|, s87
	v_add_f32_e32 v13, 1.0, v13
	s_nop 0
	v_cndmask_b32_e64 v7, v7, v8, s[0:1]
	v_cndmask_b32_e32 v8, 0, v231, vcc
	v_sub_f32_e32 v168, v7, v8
	global_load_dword v7, v[2:3], off offset:4
	s_waitcnt vmcnt(0) lgkmcnt(0)
	v_sub_f32_e32 v8, 1.0, v7
	v_fmac_f32_e32 v7, v8, v9
	v_cmp_gt_f32_e32 vcc, s12, v7
	s_nop 1
	v_cndmask_b32_e64 v8, 0, 32, vcc
	v_ldexp_f32 v8, v7, v8
	v_log_f32_e32 v8, v8
	s_nop 0
	v_mul_f32_e32 v9, 0x3f317217, v8
	v_fma_f32 v9, v8, s86, -v9
	v_fmac_f32_e32 v9, 0x3377d1cf, v8
	v_fmac_f32_e32 v9, 0x3f317217, v8
	v_cmp_lt_f32_e64 s[0:1], |v8|, s87
	s_nop 1
	v_cndmask_b32_e64 v8, v8, v9, s[0:1]
	v_cndmask_b32_e32 v9, 0, v231, vcc
	v_sub_f32_e32 v169, v8, v9
	global_load_dword v8, v[2:3], off offset:8
	v_rcp_f32_e32 v26, v11
	s_waitcnt vmcnt(0) lgkmcnt(0)
	v_sub_f32_e32 v9, 1.0, v8
	v_mul_f32_e32 v11, 1.0, v26
	v_mul_f32_e32 v25, 0xbfb8aa3b, v31
	v_exp_f32_e32 v25, v25
	v_fmac_f32_e32 v8, v11, v9
	v_add_f32_e32 v25, 1.0, v25
	v_rcp_f32_e32 v27, v25
	s_nop 0
	v_cmp_gt_f32_e32 vcc, s12, v8
	v_mul_f32_e32 v25, 1.0, v27
	s_nop 0
	v_cndmask_b32_e64 v9, 0, 32, vcc
	v_ldexp_f32 v9, v8, v9
	v_log_f32_e32 v9, v9
	s_nop 0
	v_mul_f32_e32 v11, 0x3f317217, v9
	v_fma_f32 v11, v9, s86, -v11
	v_fmac_f32_e32 v11, 0x3377d1cf, v9
	v_fmac_f32_e32 v11, 0x3f317217, v9
	v_cmp_lt_f32_e64 s[0:1], |v9|, s87
	s_nop 1
	v_cndmask_b32_e64 v9, v9, v11, s[0:1]
	v_cndmask_b32_e32 v11, 0, v231, vcc
	v_sub_f32_e32 v170, v9, v11
	global_load_dword v9, v[2:3], off offset:12
	s_waitcnt vmcnt(0) lgkmcnt(0)
	v_sub_f32_e32 v11, 1.0, v9
	v_fmac_f32_e32 v9, v25, v11
	v_cmp_gt_f32_e32 vcc, s12, v9
	s_nop 1
	v_cndmask_b32_e64 v11, 0, 32, vcc
	v_ldexp_f32 v11, v9, v11
	v_log_f32_e32 v11, v11
	s_nop 0
	v_mul_f32_e32 v25, 0x3f317217, v11
	v_fma_f32 v25, v11, s86, -v25
	v_fmac_f32_e32 v25, 0x3377d1cf, v11
	v_fmac_f32_e32 v25, 0x3f317217, v11
	v_cmp_lt_f32_e64 s[0:1], |v11|, s87
	s_nop 1
	v_cndmask_b32_e64 v11, v11, v25, s[0:1]
	v_cndmask_b32_e32 v25, 0, v231, vcc
	v_sub_f32_e32 v171, v11, v25
	ds_write_b128 v5, v[168:171]
	global_load_dword v11, v[2:3], off offset:16
	v_rcp_f32_e32 v27, v15
	s_waitcnt vmcnt(0) lgkmcnt(0)
	v_sub_f32_e32 v25, 1.0, v11
	v_mul_f32_e32 v15, 1.0, v27
	v_rcp_f32_e32 v27, v12
	v_fmac_f32_e32 v11, v15, v25
	v_cmp_gt_f32_e32 vcc, s12, v11
	v_mul_f32_e32 v26, 1.0, v27
	s_nop 0
	v_cndmask_b32_e64 v12, 0, 32, vcc
	v_ldexp_f32 v12, v11, v12
	v_log_f32_e32 v12, v12
	s_nop 0
	v_mul_f32_e32 v15, 0x3f317217, v12
	v_fma_f32 v15, v12, s86, -v15
	v_fmac_f32_e32 v15, 0x3377d1cf, v12
	v_fmac_f32_e32 v15, 0x3f317217, v12
	v_cmp_lt_f32_e64 s[0:1], |v12|, s87
	s_nop 1
	v_cndmask_b32_e64 v12, v12, v15, s[0:1]
	v_cndmask_b32_e32 v15, 0, v231, vcc
	v_sub_f32_e32 v172, v12, v15
	global_load_dword v12, v[2:3], off offset:20
	s_waitcnt vmcnt(0) lgkmcnt(0)
	v_sub_f32_e32 v15, 1.0, v12
	v_fmac_f32_e32 v12, v26, v15
	v_cmp_gt_f32_e32 vcc, s12, v12
	s_nop 1
	v_cndmask_b32_e64 v15, 0, 32, vcc
	v_ldexp_f32 v15, v12, v15
	v_log_f32_e32 v15, v15
	s_nop 0
	v_mul_f32_e32 v25, 0x3f317217, v15
	v_fma_f32 v25, v15, s86, -v25
	v_fmac_f32_e32 v25, 0x3377d1cf, v15
	v_fmac_f32_e32 v25, 0x3f317217, v15
	v_cmp_lt_f32_e64 s[0:1], |v15|, s87
	s_nop 1
	v_cndmask_b32_e64 v15, v15, v25, s[0:1]
	v_cndmask_b32_e32 v25, 0, v231, vcc
	v_sub_f32_e32 v173, v15, v25
	global_load_dword v15, v[2:3], off offset:24
	v_rcp_f32_e32 v27, v20
	s_waitcnt vmcnt(0) lgkmcnt(0)
	v_sub_f32_e32 v25, 1.0, v15
	v_mul_f32_e32 v20, 1.0, v27
	v_rcp_f32_e32 v27, v17
	v_fmac_f32_e32 v15, v20, v25
	v_cmp_gt_f32_e32 vcc, s12, v15
	v_mul_f32_e32 v26, 1.0, v27
	s_nop 0
	v_cndmask_b32_e64 v17, 0, 32, vcc
	v_ldexp_f32 v17, v15, v17
	v_log_f32_e32 v17, v17
	s_nop 0
	v_mul_f32_e32 v20, 0x3f317217, v17
	v_fma_f32 v20, v17, s86, -v20
	v_fmac_f32_e32 v20, 0x3377d1cf, v17
	v_fmac_f32_e32 v20, 0x3f317217, v17
	v_cmp_lt_f32_e64 s[0:1], |v17|, s87
	s_nop 1
	v_cndmask_b32_e64 v17, v17, v20, s[0:1]
	v_cndmask_b32_e32 v20, 0, v231, vcc
	v_sub_f32_e32 v174, v17, v20
	global_load_dword v17, v[2:3], off offset:28
	s_waitcnt vmcnt(0) lgkmcnt(0)
	v_sub_f32_e32 v20, 1.0, v17
	v_fmac_f32_e32 v17, v26, v20
	v_cmp_gt_f32_e32 vcc, s12, v17
	s_nop 1
	v_cndmask_b32_e64 v20, 0, 32, vcc
	v_ldexp_f32 v20, v17, v20
	v_log_f32_e32 v20, v20
	s_nop 0
	v_mul_f32_e32 v25, 0x3f317217, v20
	v_fma_f32 v25, v20, s86, -v25
	v_fmac_f32_e32 v25, 0x3377d1cf, v20
	v_fmac_f32_e32 v25, 0x3f317217, v20
	v_cmp_lt_f32_e64 s[0:1], |v20|, s87
	s_nop 1
	v_cndmask_b32_e64 v20, v20, v25, s[0:1]
	v_cndmask_b32_e32 v25, 0, v231, vcc
	v_sub_f32_e32 v175, v20, v25
	ds_write_b128 v5, v[172:175] offset:16
	global_load_dword v20, v[2:3], off offset:32
	v_rcp_f32_e32 v27, v24
	s_waitcnt vmcnt(0) lgkmcnt(0)
	v_sub_f32_e32 v25, 1.0, v20
	v_mul_f32_e32 v24, 1.0, v27
	v_rcp_f32_e32 v27, v21
	v_fmac_f32_e32 v20, v24, v25
	v_cmp_gt_f32_e32 vcc, s12, v20
	v_mul_f32_e32 v26, 1.0, v27
	s_nop 0
	v_cndmask_b32_e64 v21, 0, 32, vcc
	v_ldexp_f32 v21, v20, v21
	v_log_f32_e32 v21, v21
	s_nop 0
	v_mul_f32_e32 v24, 0x3f317217, v21
	v_fma_f32 v24, v21, s86, -v24
	v_fmac_f32_e32 v24, 0x3377d1cf, v21
	v_fmac_f32_e32 v24, 0x3f317217, v21
	v_cmp_lt_f32_e64 s[0:1], |v21|, s87
	s_nop 1
	v_cndmask_b32_e64 v21, v21, v24, s[0:1]
	v_cndmask_b32_e32 v24, 0, v231, vcc
	v_sub_f32_e32 v176, v21, v24
	global_load_dword v21, v[2:3], off offset:36
	s_waitcnt vmcnt(0) lgkmcnt(0)
	v_sub_f32_e32 v24, 1.0, v21
	v_fmac_f32_e32 v21, v26, v24
	v_cmp_gt_f32_e32 vcc, s12, v21
	s_nop 1
	v_cndmask_b32_e64 v24, 0, 32, vcc
	v_ldexp_f32 v24, v21, v24
	v_log_f32_e32 v24, v24
	s_nop 0
	v_mul_f32_e32 v25, 0x3f317217, v24
	v_fma_f32 v25, v24, s86, -v25
	v_fmac_f32_e32 v25, 0x3377d1cf, v24
	v_fmac_f32_e32 v25, 0x3f317217, v24
	v_cmp_lt_f32_e64 s[0:1], |v24|, s87
	s_nop 1
	v_cndmask_b32_e64 v24, v24, v25, s[0:1]
	v_cndmask_b32_e32 v25, 0, v231, vcc
	v_sub_f32_e32 v177, v24, v25
	global_load_dword v24, v[2:3], off offset:40
	v_rcp_f32_e32 v27, v23
	s_waitcnt vmcnt(0) lgkmcnt(0)
	v_sub_f32_e32 v25, 1.0, v24
	v_mul_f32_e32 v23, 1.0, v27
	v_rcp_f32_e32 v27, v22
	v_fmac_f32_e32 v24, v23, v25
	v_cmp_gt_f32_e32 vcc, s12, v24
	v_mul_f32_e32 v26, 1.0, v27
	s_nop 0
	v_cndmask_b32_e64 v22, 0, 32, vcc
	v_ldexp_f32 v22, v24, v22
	v_log_f32_e32 v22, v22
	s_nop 0
	v_mul_f32_e32 v23, 0x3f317217, v22
	v_fma_f32 v23, v22, s86, -v23
	v_fmac_f32_e32 v23, 0x3377d1cf, v22
	v_fmac_f32_e32 v23, 0x3f317217, v22
	v_cmp_lt_f32_e64 s[0:1], |v22|, s87
	s_nop 1
	v_cndmask_b32_e64 v22, v22, v23, s[0:1]
	v_cndmask_b32_e32 v23, 0, v231, vcc
	v_sub_f32_e32 v178, v22, v23
	global_load_dword v22, v[2:3], off offset:44
	s_waitcnt vmcnt(0) lgkmcnt(0)
	v_sub_f32_e32 v23, 1.0, v22
	v_fmac_f32_e32 v22, v26, v23
	v_cmp_gt_f32_e32 vcc, s12, v22
	s_nop 1
	v_cndmask_b32_e64 v23, 0, 32, vcc
	v_ldexp_f32 v23, v22, v23
	v_log_f32_e32 v23, v23
	s_nop 0
	v_mul_f32_e32 v25, 0x3f317217, v23
	v_fma_f32 v25, v23, s86, -v25
	v_fmac_f32_e32 v25, 0x3377d1cf, v23
	v_fmac_f32_e32 v25, 0x3f317217, v23
	v_cmp_lt_f32_e64 s[0:1], |v23|, s87
	s_nop 1
	v_cndmask_b32_e64 v23, v23, v25, s[0:1]
	v_cndmask_b32_e32 v25, 0, v231, vcc
	v_sub_f32_e32 v179, v23, v25
	ds_write_b128 v5, v[176:179] offset:32
	global_load_dword v23, v[2:3], off offset:48
	v_rcp_f32_e32 v27, v19
	s_waitcnt vmcnt(0) lgkmcnt(0)
	v_sub_f32_e32 v25, 1.0, v23
	v_mul_f32_e32 v19, 1.0, v27
	v_rcp_f32_e32 v27, v18
	v_fmac_f32_e32 v23, v19, v25
	v_cmp_gt_f32_e32 vcc, s12, v23
	v_mul_f32_e32 v26, 1.0, v27
	s_nop 0
	v_cndmask_b32_e64 v18, 0, 32, vcc
	v_ldexp_f32 v18, v23, v18
	v_log_f32_e32 v18, v18
	s_nop 0
	v_mul_f32_e32 v19, 0x3f317217, v18
	v_fma_f32 v19, v18, s86, -v19
	v_fmac_f32_e32 v19, 0x3377d1cf, v18
	v_fmac_f32_e32 v19, 0x3f317217, v18
	v_cmp_lt_f32_e64 s[0:1], |v18|, s87
	s_nop 1
	v_cndmask_b32_e64 v18, v18, v19, s[0:1]
	v_cndmask_b32_e32 v19, 0, v231, vcc
	v_sub_f32_e32 v180, v18, v19
	global_load_dword v18, v[2:3], off offset:52
	s_waitcnt vmcnt(0) lgkmcnt(0)
	v_sub_f32_e32 v19, 1.0, v18
	v_fmac_f32_e32 v18, v26, v19
	v_cmp_gt_f32_e32 vcc, s12, v18
	s_nop 1
	v_cndmask_b32_e64 v19, 0, 32, vcc
	v_ldexp_f32 v19, v18, v19
	v_log_f32_e32 v19, v19
	s_nop 0
	v_mul_f32_e32 v25, 0x3f317217, v19
	v_fma_f32 v25, v19, s86, -v25
	v_fmac_f32_e32 v25, 0x3377d1cf, v19
	v_fmac_f32_e32 v25, 0x3f317217, v19
	v_cmp_lt_f32_e64 s[0:1], |v19|, s87
	s_nop 1
	v_cndmask_b32_e64 v19, v19, v25, s[0:1]
	v_cndmask_b32_e32 v25, 0, v231, vcc
	v_sub_f32_e32 v181, v19, v25
	global_load_dword v25, v[2:3], off offset:56
	v_rcp_f32_e32 v27, v14
	s_waitcnt vmcnt(0) lgkmcnt(0)
	v_sub_f32_e32 v19, 1.0, v25
	v_mul_f32_e32 v14, 1.0, v27
	v_rcp_f32_e32 v27, v13
	v_fmac_f32_e32 v25, v14, v19
	v_cmp_gt_f32_e32 vcc, s12, v25
	v_mul_f32_e32 v13, 1.0, v27
	s_nop 0
	v_cndmask_b32_e64 v14, 0, 32, vcc
	v_ldexp_f32 v14, v25, v14
	v_log_f32_e32 v14, v14
	s_nop 0
	v_mul_f32_e32 v19, 0x3f317217, v14
	v_fma_f32 v19, v14, s86, -v19
	v_fmac_f32_e32 v19, 0x3377d1cf, v14
	v_fmac_f32_e32 v19, 0x3f317217, v14
	v_cmp_lt_f32_e64 s[0:1], |v14|, s87
	s_nop 1
	v_cndmask_b32_e64 v14, v14, v19, s[0:1]
	v_cndmask_b32_e32 v19, 0, v231, vcc
	v_sub_f32_e32 v182, v14, v19
	global_load_dword v3, v[2:3], off offset:60
	s_waitcnt vmcnt(0) lgkmcnt(0)
	v_sub_f32_e32 v2, 1.0, v3
	v_fmac_f32_e32 v3, v13, v2
	v_cmp_gt_f32_e32 vcc, s12, v3
	s_nop 1
	v_cndmask_b32_e64 v2, 0, 32, vcc
	v_ldexp_f32 v2, v3, v2
	v_log_f32_e32 v2, v2
	s_nop 0
	v_mul_f32_e32 v13, 0x3f317217, v2
	v_fma_f32 v13, v2, s86, -v13
	v_fmac_f32_e32 v13, 0x3377d1cf, v2
	v_fmac_f32_e32 v13, 0x3f317217, v2
	v_cmp_lt_f32_e64 s[0:1], |v2|, s87
	s_nop 1
	v_cndmask_b32_e64 v2, v2, v13, s[0:1]
	v_cndmask_b32_e32 v13, 0, v231, vcc
	v_sub_f32_e32 v183, v2, v13
	v_ashrrev_i32_e32 v13, 7, v10
	v_and_b32_e32 v10, 0x7f, v10
	v_lshlrev_b32_e32 v14, 13, v13
	v_lshlrev_b32_e32 v19, 2, v10
	ds_write_b128 v5, v[180:183] offset:48
	v_add3_u32 v2, 0, v19, v14
	s_mov_b64 s[0:1], -1
	s_and_b64 vcc, exec, s[2:3]
	s_waitcnt lgkmcnt(0)
	s_barrier
	s_cbranch_vccz .LBB0_598
	ds_read2st64_b32 v[26:27], v2 offset0:28 offset1:30
	s_mov_b64 s[0:1], 0
	s_waitcnt lgkmcnt(0)
	v_add_f32_e32 v27, 0, v27
	v_add_f32_e32 v28, v27, v26
	ds_write2st64_b32 v2, v28, v27 offset0:28 offset1:30
	ds_read2st64_b32 v[26:27], v2 offset0:24 offset1:26
	s_waitcnt lgkmcnt(0)
	v_add_f32_e32 v27, v28, v27
	v_add_f32_e32 v28, v27, v26
	ds_write2st64_b32 v2, v28, v27 offset0:24 offset1:26
	ds_read2st64_b32 v[26:27], v2 offset0:20 offset1:22
	s_waitcnt lgkmcnt(0)
	v_add_f32_e32 v27, v28, v27
	v_add_f32_e32 v28, v27, v26
	ds_write2st64_b32 v2, v28, v27 offset0:20 offset1:22
	ds_read2st64_b32 v[26:27], v2 offset0:16 offset1:18
	s_waitcnt lgkmcnt(0)
	v_add_f32_e32 v27, v28, v27
	v_add_f32_e32 v28, v27, v26
	ds_write2st64_b32 v2, v28, v27 offset0:16 offset1:18
	ds_read2st64_b32 v[26:27], v2 offset0:12 offset1:14
	s_waitcnt lgkmcnt(0)
	v_add_f32_e32 v27, v28, v27
	v_add_f32_e32 v28, v27, v26
	ds_write2st64_b32 v2, v28, v27 offset0:12 offset1:14
	ds_read2st64_b32 v[26:27], v2 offset0:8 offset1:10
	s_waitcnt lgkmcnt(0)
	v_add_f32_e32 v27, v28, v27
	v_add_f32_e32 v28, v27, v26
	ds_write2st64_b32 v2, v28, v27 offset0:8 offset1:10
	ds_read2st64_b32 v[26:27], v2 offset0:4 offset1:6
	s_waitcnt lgkmcnt(0)
	v_add_f32_e32 v27, v28, v27
	v_add_f32_e32 v28, v27, v26
	ds_write2st64_b32 v2, v28, v27 offset0:4 offset1:6
	ds_read2st64_b32 v[26:27], v2 offset1:2
	s_waitcnt lgkmcnt(0)
	v_add_f32_e32 v27, v28, v27
	v_add_f32_e32 v26, v27, v26
	ds_write2st64_b32 v2, v26, v27 offset1:2

.LBB0_736:
	s_xor_b64 s[18:19], s[92:93], -1
	s_or_b32 s0, s95, s23
	s_mul_hi_i32 s8, s0, 0x84
	s_mul_i32 s9, s0, 0x84
	s_and_b64 s[0:1], s[92:93], exec
	s_cselect_b32 s0, s21, s94
	s_ashr_i32 s1, s0, 31
	s_add_u32 s0, s9, s0
	s_addc_u32 s1, s8, s1
	s_lshl_b64 s[0:1], s[0:1], 15
	v_lshl_add_u64 v[16:17], v[86:87], 0, s[0:1]
	global_load_dwordx4 v[60:63], v[16:17], off
	global_load_dwordx4 v[56:59], v[16:17], off offset:32
	global_load_dwordx4 v[52:55], v[16:17], off offset:64
	global_load_dwordx4 v[48:51], v[16:17], off offset:96
	global_load_dwordx4 v[44:47], v[16:17], off offset:128
	global_load_dwordx4 v[40:43], v[16:17], off offset:160
	global_load_dwordx4 v[36:39], v[16:17], off offset:192
	global_load_dwordx4 v[32:35], v[16:17], off offset:224
	v_mov_b32_e32 v113, v207
	s_and_b64 vcc, exec, s[96:97]
	v_ashrrev_i32_e32 v110, 3, v113
	v_lshlrev_b32_e32 v16, 4, v113
	v_and_b32_e32 v111, 0x70, v16
	v_add_u32_e32 v18, s22, v110
	v_mov_b64_e32 v[16:17], s[2:3]
	v_mad_i64_i32 v[16:17], s[0:1], v18, s14, v[16:17]
	v_lshlrev_b32_e32 v128, 1, v111
	v_lshl_add_u64 v[90:91], v[16:17], 0, v[128:129]
	v_lshlrev_b32_e32 v16, 9, v110
	v_lshlrev_b32_e32 v17, 2, v111
	v_add3_u32 v109, 0, v16, v17
	s_mov_b64 s[0:1], -1
	s_cbranch_vccz .LBB0_754
	s_and_b64 s[0:1], s[92:93], exec
	s_cselect_b32 s26, s15, 0x1800
	v_lshl_add_u64 v[20:21], v[90:91], 0, s[26:27]
	global_load_dwordx4 v[16:19], v[20:21], off
	global_load_dwordx4 v[116:119], v[20:21], off offset:16
	s_waitcnt vmcnt(0) lgkmcnt(0)
	v_lshlrev_b32_e32 v20, 16, v16
	v_and_b32_e32 v112, 0xffff0000, v16
	v_or_b32_e32 v16, s20, v111
	v_lshlrev_b32_e32 v128, 2, v16
	v_lshlrev_b32_e32 v115, 16, v17
	v_and_b32_e32 v120, 0xffff0000, v17
	v_lshl_add_u64 v[16:17], s[78:79], 0, v[128:129]
	global_load_dword v111, v[16:17], off
	v_lshlrev_b32_e32 v31, 16, v19
	v_and_b32_e32 v30, 0xffff0000, v19
	v_mul_f32_e32 v19, 0xbfb8aa3b, v20
	v_exp_f32_e32 v19, v19
	v_lshlrev_b32_e32 v29, 16, v116
	v_and_b32_e32 v28, 0xffff0000, v116
	v_lshlrev_b32_e32 v27, 16, v117
	v_add_f32_e32 v19, 1.0, v19
	v_rcp_f32_e32 v116, v19
	v_and_b32_e32 v26, 0xffff0000, v117
	v_lshlrev_b32_e32 v25, 16, v118
	v_and_b32_e32 v24, 0xffff0000, v118
	v_lshlrev_b32_e32 v23, 16, v119
	v_and_b32_e32 v22, 0xffff0000, v119
	v_mul_f32_e32 v19, 1.0, v116
	v_mul_f32_e32 v20, 0xbfb8aa3b, v112
	v_exp_f32_e32 v20, v20
	v_lshlrev_b32_e32 v114, 16, v18
	v_and_b32_e32 v21, 0xffff0000, v18
	v_mul_f32_e32 v114, 0xbfb8aa3b, v114
	v_add_f32_e32 v20, 1.0, v20
	v_rcp_f32_e32 v116, v20
	v_exp_f32_e32 v114, v114
	v_mul_f32_e32 v21, 0xbfb8aa3b, v21
	v_exp_f32_e32 v21, v21
	v_mul_f32_e32 v20, 1.0, v116
	v_add_f32_e32 v114, 1.0, v114
	v_add_f32_e32 v21, 1.0, v21
	v_mul_f32_e32 v31, 0xbfb8aa3b, v31
	v_exp_f32_e32 v31, v31
	v_mul_f32_e32 v30, 0xbfb8aa3b, v30
	v_exp_f32_e32 v30, v30
	v_mul_f32_e32 v29, 0xbfb8aa3b, v29
	v_add_f32_e32 v31, 1.0, v31
	v_exp_f32_e32 v29, v29
	v_add_f32_e32 v30, 1.0, v30
	v_mul_f32_e32 v28, 0xbfb8aa3b, v28
	v_exp_f32_e32 v28, v28
	v_add_f32_e32 v29, 1.0, v29
	v_mul_f32_e32 v27, 0xbfb8aa3b, v27
	v_exp_f32_e32 v27, v27
	v_add_f32_e32 v28, 1.0, v28
	v_mul_f32_e32 v26, 0xbfb8aa3b, v26
	v_exp_f32_e32 v26, v26
	v_add_f32_e32 v27, 1.0, v27
	v_mul_f32_e32 v25, 0xbfb8aa3b, v25
	v_exp_f32_e32 v25, v25
	v_add_f32_e32 v26, 1.0, v26
	v_mul_f32_e32 v24, 0xbfb8aa3b, v24
	v_exp_f32_e32 v24, v24
	v_add_f32_e32 v25, 1.0, v25
	v_mul_f32_e32 v23, 0xbfb8aa3b, v23
	v_exp_f32_e32 v23, v23
	v_add_f32_e32 v24, 1.0, v24
	v_mul_f32_e32 v22, 0xbfb8aa3b, v22
	v_exp_f32_e32 v22, v22
	v_add_f32_e32 v23, 1.0, v23
	s_waitcnt vmcnt(0) lgkmcnt(0)
	v_sub_f32_e32 v18, 1.0, v111
	v_fmac_f32_e32 v111, v18, v19
	v_cmp_gt_f32_e32 vcc, s12, v111
	v_add_f32_e32 v22, 1.0, v22
	s_nop 0
	v_cndmask_b32_e64 v18, 0, 32, vcc
	v_ldexp_f32 v18, v111, v18
	v_log_f32_e32 v18, v18
	s_nop 0
	v_mul_f32_e32 v19, 0x3f317217, v18
	v_fma_f32 v19, v18, s86, -v19
	v_fmac_f32_e32 v19, 0x3377d1cf, v18
	v_fmac_f32_e32 v19, 0x3f317217, v18
	v_cmp_lt_f32_e64 s[0:1], |v18|, s87
	s_nop 1
	v_cndmask_b32_e64 v18, v18, v19, s[0:1]
	v_cndmask_b32_e32 v19, 0, v231, vcc
	v_sub_f32_e32 v168, v18, v19
	global_load_dword v112, v[16:17], off offset:4
	s_waitcnt vmcnt(0) lgkmcnt(0)
	v_sub_f32_e32 v18, 1.0, v112
	v_fmac_f32_e32 v112, v18, v20
	v_cmp_gt_f32_e32 vcc, s12, v112
	v_mul_f32_e32 v20, 0xbfb8aa3b, v115
	v_exp_f32_e32 v20, v20
	v_cndmask_b32_e64 v18, 0, 32, vcc
	v_ldexp_f32 v18, v112, v18
	v_log_f32_e32 v18, v18
	v_add_f32_e32 v20, 1.0, v20
	v_mul_f32_e32 v19, 0x3f317217, v18
	v_fma_f32 v19, v18, s86, -v19
	v_fmac_f32_e32 v19, 0x3377d1cf, v18
	v_fmac_f32_e32 v19, 0x3f317217, v18
	v_cmp_lt_f32_e64 s[0:1], |v18|, s87
	s_nop 1
	v_cndmask_b32_e64 v18, v18, v19, s[0:1]
	v_cndmask_b32_e32 v19, 0, v231, vcc
	v_sub_f32_e32 v169, v18, v19
	global_load_dword v18, v[16:17], off offset:8
	v_rcp_f32_e32 v116, v20
	s_waitcnt vmcnt(0) lgkmcnt(0)
	v_sub_f32_e32 v19, 1.0, v18
	v_mul_f32_e32 v20, 1.0, v116
	v_mul_f32_e32 v115, 0xbfb8aa3b, v120
	v_exp_f32_e32 v115, v115
	v_fmac_f32_e32 v18, v20, v19
	v_add_f32_e32 v115, 1.0, v115
	v_rcp_f32_e32 v117, v115
	s_nop 0
	v_cmp_gt_f32_e32 vcc, s12, v18
	v_mul_f32_e32 v115, 1.0, v117
	s_nop 0
	v_cndmask_b32_e64 v19, 0, 32, vcc
	v_ldexp_f32 v19, v18, v19
	v_log_f32_e32 v19, v19
	s_nop 0
	v_mul_f32_e32 v20, 0x3f317217, v19
	v_fma_f32 v20, v19, s86, -v20
	v_fmac_f32_e32 v20, 0x3377d1cf, v19
	v_fmac_f32_e32 v20, 0x3f317217, v19
	v_cmp_lt_f32_e64 s[0:1], |v19|, s87
	s_nop 1
	v_cndmask_b32_e64 v19, v19, v20, s[0:1]
	v_cndmask_b32_e32 v20, 0, v231, vcc
	v_sub_f32_e32 v170, v19, v20
	global_load_dword v19, v[16:17], off offset:12
	s_waitcnt vmcnt(0) lgkmcnt(0)
	v_sub_f32_e32 v20, 1.0, v19
	v_fmac_f32_e32 v19, v115, v20
	v_cmp_gt_f32_e32 vcc, s12, v19
	s_nop 1
	v_cndmask_b32_e64 v20, 0, 32, vcc
	v_ldexp_f32 v20, v19, v20
	v_log_f32_e32 v20, v20
	s_nop 0
	v_mul_f32_e32 v115, 0x3f317217, v20
	v_fma_f32 v115, v20, s86, -v115
	v_fmac_f32_e32 v115, 0x3377d1cf, v20
	v_fmac_f32_e32 v115, 0x3f317217, v20
	v_cmp_lt_f32_e64 s[0:1], |v20|, s87
	s_nop 1
	v_cndmask_b32_e64 v20, v20, v115, s[0:1]
	v_cndmask_b32_e32 v115, 0, v231, vcc
	v_sub_f32_e32 v171, v20, v115
	ds_write_b128 v109, v[168:171]
	global_load_dword v20, v[16:17], off offset:16
	v_rcp_f32_e32 v117, v114
	s_waitcnt vmcnt(0) lgkmcnt(0)
	v_sub_f32_e32 v115, 1.0, v20
	v_mul_f32_e32 v114, 1.0, v117
	v_rcp_f32_e32 v117, v21
	v_fmac_f32_e32 v20, v114, v115
	v_cmp_gt_f32_e32 vcc, s12, v20
	v_mul_f32_e32 v116, 1.0, v117
	s_nop 0
	v_cndmask_b32_e64 v21, 0, 32, vcc
	v_ldexp_f32 v21, v20, v21
	v_log_f32_e32 v21, v21
	s_nop 0
	v_mul_f32_e32 v114, 0x3f317217, v21
	v_fma_f32 v114, v21, s86, -v114
	v_fmac_f32_e32 v114, 0x3377d1cf, v21
	v_fmac_f32_e32 v114, 0x3f317217, v21
	v_cmp_lt_f32_e64 s[0:1], |v21|, s87
	s_nop 1
	v_cndmask_b32_e64 v21, v21, v114, s[0:1]
	v_cndmask_b32_e32 v114, 0, v231, vcc
	v_sub_f32_e32 v172, v21, v114
	global_load_dword v21, v[16:17], off offset:20
	s_waitcnt vmcnt(0) lgkmcnt(0)
	v_sub_f32_e32 v114, 1.0, v21
	v_fmac_f32_e32 v21, v116, v114
	v_cmp_gt_f32_e32 vcc, s12, v21
	s_nop 1
	v_cndmask_b32_e64 v114, 0, 32, vcc
	v_ldexp_f32 v114, v21, v114
	v_log_f32_e32 v114, v114
	s_nop 0
	v_mul_f32_e32 v115, 0x3f317217, v114
	v_fma_f32 v115, v114, s86, -v115
	v_fmac_f32_e32 v115, 0x3377d1cf, v114
	v_fmac_f32_e32 v115, 0x3f317217, v114
	v_cmp_lt_f32_e64 s[0:1], |v114|, s87
	s_nop 1
	v_cndmask_b32_e64 v114, v114, v115, s[0:1]
	v_cndmask_b32_e32 v115, 0, v231, vcc
	v_sub_f32_e32 v173, v114, v115
	global_load_dword v114, v[16:17], off offset:24
	v_rcp_f32_e32 v117, v31
	s_waitcnt vmcnt(0) lgkmcnt(0)
	v_sub_f32_e32 v115, 1.0, v114
	v_mul_f32_e32 v31, 1.0, v117
	v_rcp_f32_e32 v117, v30
	v_fmac_f32_e32 v114, v31, v115
	v_cmp_gt_f32_e32 vcc, s12, v114
	v_mul_f32_e32 v30, 1.0, v117
	s_nop 0
	v_cndmask_b32_e64 v31, 0, 32, vcc
	v_ldexp_f32 v31, v114, v31
	v_log_f32_e32 v31, v31
	s_nop 0
	v_mul_f32_e32 v115, 0x3f317217, v31
	v_fma_f32 v115, v31, s86, -v115
	v_fmac_f32_e32 v115, 0x3377d1cf, v31
	v_fmac_f32_e32 v115, 0x3f317217, v31
	v_cmp_lt_f32_e64 s[0:1], |v31|, s87
	s_nop 1
	v_cndmask_b32_e64 v31, v31, v115, s[0:1]
	v_cndmask_b32_e32 v115, 0, v231, vcc
	v_sub_f32_e32 v174, v31, v115
	global_load_dword v115, v[16:17], off offset:28
	s_waitcnt vmcnt(0) lgkmcnt(0)
	v_sub_f32_e32 v31, 1.0, v115
	v_fmac_f32_e32 v115, v30, v31
	v_cmp_gt_f32_e32 vcc, s12, v115
	s_nop 1
	v_cndmask_b32_e64 v30, 0, 32, vcc
	v_ldexp_f32 v30, v115, v30
	v_log_f32_e32 v30, v30
	s_nop 0
	v_mul_f32_e32 v31, 0x3f317217, v30
	v_fma_f32 v31, v30, s86, -v31
	v_fmac_f32_e32 v31, 0x3377d1cf, v30
	v_fmac_f32_e32 v31, 0x3f317217, v30
	v_cmp_lt_f32_e64 s[0:1], |v30|, s87
	s_nop 1
	v_cndmask_b32_e64 v30, v30, v31, s[0:1]
	v_cndmask_b32_e32 v31, 0, v231, vcc
	v_sub_f32_e32 v175, v30, v31
	ds_write_b128 v109, v[172:175] offset:16
	global_load_dword v116, v[16:17], off offset:32
	v_rcp_f32_e32 v117, v29
	s_waitcnt vmcnt(0) lgkmcnt(0)
	v_sub_f32_e32 v30, 1.0, v116
	v_mul_f32_e32 v29, 1.0, v117
	v_rcp_f32_e32 v117, v28
	v_fmac_f32_e32 v116, v29, v30
	v_cmp_gt_f32_e32 vcc, s12, v116
	v_mul_f32_e32 v28, 1.0, v117
	s_nop 0
	v_cndmask_b32_e64 v29, 0, 32, vcc
	v_ldexp_f32 v29, v116, v29
	v_log_f32_e32 v29, v29
	s_nop 0
	v_mul_f32_e32 v30, 0x3f317217, v29
	v_fma_f32 v30, v29, s86, -v30
	v_fmac_f32_e32 v30, 0x3377d1cf, v29
	v_fmac_f32_e32 v30, 0x3f317217, v29
	v_cmp_lt_f32_e64 s[0:1], |v29|, s87
	s_nop 1
	v_cndmask_b32_e64 v29, v29, v30, s[0:1]
	v_cndmask_b32_e32 v30, 0, v231, vcc
	v_sub_f32_e32 v176, v29, v30
	global_load_dword v117, v[16:17], off offset:36
	s_waitcnt vmcnt(0) lgkmcnt(0)
	v_sub_f32_e32 v29, 1.0, v117
	v_fmac_f32_e32 v117, v28, v29
	v_cmp_gt_f32_e32 vcc, s12, v117
	s_nop 1
	v_cndmask_b32_e64 v28, 0, 32, vcc
	v_ldexp_f32 v28, v117, v28
	v_log_f32_e32 v28, v28
	s_nop 0
	v_mul_f32_e32 v29, 0x3f317217, v28
	v_fma_f32 v29, v28, s86, -v29
	v_fmac_f32_e32 v29, 0x3377d1cf, v28
	v_fmac_f32_e32 v29, 0x3f317217, v28
	v_cmp_lt_f32_e64 s[0:1], |v28|, s87
	s_nop 1
	v_cndmask_b32_e64 v28, v28, v29, s[0:1]
	v_cndmask_b32_e32 v29, 0, v231, vcc
	v_sub_f32_e32 v177, v28, v29
	global_load_dword v118, v[16:17], off offset:40
	v_rcp_f32_e32 v30, v27
	s_waitcnt vmcnt(0) lgkmcnt(0)
	v_sub_f32_e32 v28, 1.0, v118
	v_mul_f32_e32 v27, 1.0, v30
	v_rcp_f32_e32 v30, v26
	v_fmac_f32_e32 v118, v27, v28
	v_cmp_gt_f32_e32 vcc, s12, v118
	v_mul_f32_e32 v29, 1.0, v30
	s_nop 0
	v_cndmask_b32_e64 v26, 0, 32, vcc
	v_ldexp_f32 v26, v118, v26
	v_log_f32_e32 v26, v26
	s_nop 0
	v_mul_f32_e32 v27, 0x3f317217, v26
	v_fma_f32 v27, v26, s86, -v27
	v_fmac_f32_e32 v27, 0x3377d1cf, v26
	v_fmac_f32_e32 v27, 0x3f317217, v26
	v_cmp_lt_f32_e64 s[0:1], |v26|, s87
	s_nop 1
	v_cndmask_b32_e64 v26, v26, v27, s[0:1]
	v_cndmask_b32_e32 v27, 0, v231, vcc
	v_sub_f32_e32 v178, v26, v27
	global_load_dword v26, v[16:17], off offset:44
	s_waitcnt vmcnt(0) lgkmcnt(0)
	v_sub_f32_e32 v27, 1.0, v26
	v_fmac_f32_e32 v26, v29, v27
	v_cmp_gt_f32_e32 vcc, s12, v26
	s_nop 1
	v_cndmask_b32_e64 v27, 0, 32, vcc
	v_ldexp_f32 v27, v26, v27
	v_log_f32_e32 v27, v27
	s_nop 0
	v_mul_f32_e32 v28, 0x3f317217, v27
	v_fma_f32 v28, v27, s86, -v28
	v_fmac_f32_e32 v28, 0x3377d1cf, v27
	v_fmac_f32_e32 v28, 0x3f317217, v27
	v_cmp_lt_f32_e64 s[0:1], |v27|, s87
	s_nop 1
	v_cndmask_b32_e64 v27, v27, v28, s[0:1]
	v_cndmask_b32_e32 v28, 0, v231, vcc
	v_sub_f32_e32 v179, v27, v28
	ds_write_b128 v109, v[176:179] offset:32
	global_load_dword v27, v[16:17], off offset:48
	v_rcp_f32_e32 v30, v25
	s_waitcnt vmcnt(0) lgkmcnt(0)
	v_sub_f32_e32 v28, 1.0, v27
	v_mul_f32_e32 v25, 1.0, v30
	v_rcp_f32_e32 v30, v24
	v_fmac_f32_e32 v27, v25, v28
	v_cmp_gt_f32_e32 vcc, s12, v27
	v_mul_f32_e32 v29, 1.0, v30
	s_nop 0
	v_cndmask_b32_e64 v24, 0, 32, vcc
	v_ldexp_f32 v24, v27, v24
	v_log_f32_e32 v24, v24
	s_nop 0
	v_mul_f32_e32 v25, 0x3f317217, v24
	v_fma_f32 v25, v24, s86, -v25
	v_fmac_f32_e32 v25, 0x3377d1cf, v24
	v_fmac_f32_e32 v25, 0x3f317217, v24
	v_cmp_lt_f32_e64 s[0:1], |v24|, s87
	s_nop 1
	v_cndmask_b32_e64 v24, v24, v25, s[0:1]
	v_cndmask_b32_e32 v25, 0, v231, vcc
	v_sub_f32_e32 v180, v24, v25
	global_load_dword v24, v[16:17], off offset:52
	s_waitcnt vmcnt(0) lgkmcnt(0)
	v_sub_f32_e32 v25, 1.0, v24
	v_fmac_f32_e32 v24, v29, v25
	v_cmp_gt_f32_e32 vcc, s12, v24
	s_nop 1
	v_cndmask_b32_e64 v25, 0, 32, vcc
	v_ldexp_f32 v25, v24, v25
	v_log_f32_e32 v25, v25
	s_nop 0
	v_mul_f32_e32 v28, 0x3f317217, v25
	v_fma_f32 v28, v25, s86, -v28
	v_fmac_f32_e32 v28, 0x3377d1cf, v25
	v_fmac_f32_e32 v28, 0x3f317217, v25
	v_cmp_lt_f32_e64 s[0:1], |v25|, s87
	s_nop 1
	v_cndmask_b32_e64 v25, v25, v28, s[0:1]
	v_cndmask_b32_e32 v28, 0, v231, vcc
	v_sub_f32_e32 v181, v25, v28
	global_load_dword v25, v[16:17], off offset:56
	v_rcp_f32_e32 v30, v23
	s_waitcnt vmcnt(0) lgkmcnt(0)
	v_sub_f32_e32 v28, 1.0, v25
	v_mul_f32_e32 v23, 1.0, v30
	v_rcp_f32_e32 v30, v22
	v_fmac_f32_e32 v25, v23, v28
	v_cmp_gt_f32_e32 vcc, s12, v25
	v_mul_f32_e32 v22, 1.0, v30
	s_nop 0
	v_cndmask_b32_e64 v23, 0, 32, vcc
	v_ldexp_f32 v23, v25, v23
	v_log_f32_e32 v23, v23
	s_nop 0
	v_mul_f32_e32 v28, 0x3f317217, v23
	v_fma_f32 v28, v23, s86, -v28
	v_fmac_f32_e32 v28, 0x3377d1cf, v23
	v_fmac_f32_e32 v28, 0x3f317217, v23
	v_cmp_lt_f32_e64 s[0:1], |v23|, s87
	s_nop 1
	v_cndmask_b32_e64 v23, v23, v28, s[0:1]
	v_cndmask_b32_e32 v28, 0, v231, vcc
	v_sub_f32_e32 v182, v23, v28
	global_load_dword v16, v[16:17], off offset:60
	s_waitcnt vmcnt(0) lgkmcnt(0)
	v_sub_f32_e32 v17, 1.0, v16
	v_fmac_f32_e32 v16, v22, v17
	v_cmp_gt_f32_e32 vcc, s12, v16
	s_nop 1
	v_cndmask_b32_e64 v17, 0, 32, vcc
	v_ldexp_f32 v17, v16, v17
	v_log_f32_e32 v17, v17
	s_nop 0
	v_mul_f32_e32 v22, 0x3f317217, v17
	v_fma_f32 v22, v17, s86, -v22
	v_fmac_f32_e32 v22, 0x3377d1cf, v17
	v_fmac_f32_e32 v22, 0x3f317217, v17
	v_cmp_lt_f32_e64 s[0:1], |v17|, s87
	s_nop 1
	v_cndmask_b32_e64 v17, v17, v22, s[0:1]
	v_cndmask_b32_e32 v22, 0, v231, vcc
	v_sub_f32_e32 v183, v17, v22
	ds_write_b128 v109, v[180:183] offset:48
	v_ashrrev_i32_e32 v17, 7, v113
	v_and_b32_e32 v22, 0x7f, v113
	v_lshlrev_b32_e32 v23, 13, v17
	v_lshlrev_b32_e32 v28, 2, v22
	v_add3_u32 v113, 0, v28, v23
	s_mov_b64 s[0:1], -1
	s_and_b64 vcc, exec, s[18:19]
	s_waitcnt lgkmcnt(0)
	s_barrier
	s_cbranch_vccz .LBB0_739
	ds_read2st64_b32 v[30:31], v113 offset0:28 offset1:30
	s_mov_b64 s[0:1], 0
	s_waitcnt lgkmcnt(0)
	v_add_f32_e32 v29, 0, v31
	v_add_f32_e32 v119, v29, v30
	ds_read2st64_b32 v[30:31], v113 offset0:24 offset1:26
	ds_write2st64_b32 v113, v119, v29 offset0:28 offset1:30
	s_waitcnt lgkmcnt(1)
	v_add_f32_e32 v29, v119, v31
	v_add_f32_e32 v119, v29, v30
	ds_read2st64_b32 v[30:31], v113 offset0:20 offset1:22
	ds_write2st64_b32 v113, v119, v29 offset0:24 offset1:26
	s_waitcnt lgkmcnt(1)
	v_add_f32_e32 v29, v119, v31
	v_add_f32_e32 v119, v29, v30
	ds_read2st64_b32 v[30:31], v113 offset0:16 offset1:18
	ds_write2st64_b32 v113, v119, v29 offset0:20 offset1:22
	s_waitcnt lgkmcnt(1)
	v_add_f32_e32 v29, v119, v31
	v_add_f32_e32 v119, v29, v30
	ds_read2st64_b32 v[30:31], v113 offset0:12 offset1:14
	ds_write2st64_b32 v113, v119, v29 offset0:16 offset1:18
	s_waitcnt lgkmcnt(1)
	v_add_f32_e32 v29, v119, v31
	v_add_f32_e32 v119, v29, v30
	ds_read2st64_b32 v[30:31], v113 offset0:8 offset1:10
	ds_write2st64_b32 v113, v119, v29 offset0:12 offset1:14
	s_waitcnt lgkmcnt(1)
	v_add_f32_e32 v29, v119, v31
	v_add_f32_e32 v119, v29, v30
	ds_read2st64_b32 v[30:31], v113 offset0:4 offset1:6
	ds_write2st64_b32 v113, v119, v29 offset0:8 offset1:10
	s_waitcnt lgkmcnt(1)
	v_add_f32_e32 v29, v119, v31
	v_add_f32_e32 v119, v29, v30
	ds_read2st64_b32 v[30:31], v113 offset1:2
	ds_write2st64_b32 v113, v119, v29 offset0:4 offset1:6
	s_waitcnt lgkmcnt(1)
	v_add_f32_e32 v29, v119, v31
	v_add_f32_e32 v30, v29, v30
	ds_write2st64_b32 v113, v30, v29 offset1:2
